# GEMM K-loops 1 and 3: loop-control and next-iteration pointer selects hoisted from the loop edge into SALU slots of the last MFMA block
# speedup vs baseline: 1.0162x; 1.0034x over previous
; #define PG8_STAGE(bufoff, gbase, voff) do { _Pragma("unroll") for (int _i = 0; _i < 2; ++_i) \
;         __builtin_amdgcn_global_load_lds((const unsigned*)((const char*)(gbase) + (voff)[_i]), (PG8_LAS unsigned*)(lds + (bufoff) + ldsw + _i * 8192), 16, 0, 0); } while (0)
; #define PG8_LDA(dst, b, h) do { _Pragma("unroll") for (int m = 0; m < 4; ++m) _Pragma("unroll") for (int k = 0; k < 2; ++k) dst[m][k] = *(const PG8_LAS bf16x8*)(lds + PG8_SA(b, h) + aoff + m * 2048 + k * 1024); } while (0)
; #define PG8_LDB(dst, b, h) do { _Pragma("unroll") for (int n = 0; n < 2; ++n) _Pragma("unroll") for (int k = 0; k < 2; ++k) dst[n][k] = *(const PG8_LAS bf16x8*)(lds + PG8_SB(b, h) + boff + n * 2048 + k * 1024); } while (0)
; #define PG8_WAIT_V(n) asm volatile("s_waitcnt vmcnt(" #n ")" ::: "memory")
; #define PG8_WAIT_L(n) asm volatile("s_waitcnt lgkmcnt(" #n ")" ::: "memory")
; #define PG8_BAR __builtin_amdgcn_s_barrier()
; template <class Epi, class Sched, bool ALIGN_EPI = false, bool SP2 = false>
; __device__ __forceinline__ void gemm_phase(PG8_LAS unsigned char* lds, const Gemm g, const Sched& S, const Epi& E) {
;     ...
;     for (;;) {
;         const bool has_next = S.next(ui + 1, nxt);
;         const char* nA = has_next ? (const char*)g.A + (size_t)nxt.pm * tstep : cA; const char* nB = has_next ? (const char*)g.Bt + (size_t)nxt.pn * tstep : cB;
;         for (int t = 0; t < nt; t += 2) {
;             const bool last = (t == nt - 2);
;             const char* a1 = cA + (size_t)(t + 1) * kstep;
;             const char* a2 = last ? nA : cA + (size_t)(t + 2) * kstep; const char* b2 = last ? nB : cB + (size_t)(t + 2) * kstep;
;             const char* a3 = a2 + kstep; const char* b3 = b2 + kstep;
;             if (last && has_next) S.a_ready(nxt);
;             if constexpr (SP2) {
;             PG8_LDB(B0, 0, 0); PG8_LDB(B1, 0, 1); PG8_SCHED; PG8_LDA(At, 0, 0); PG8_STAGE(PG8_SA(1, 1), a1 + hstep, voffA);
;             PG8_WAIT_V(8); PG8_WAIT_L(0); PG8_BAR; PG8_MMA(0, 0, At, B0); PG8_MMA(0, 1, At, B1); PG8_BAR; PG8_SCHED;
;     ...
; #pragma unroll
;         for (int a = 0; a < 2; ++a)
; #pragma unroll
;             for (int b = 0; b < 2; ++b)
; #pragma unroll
;                 for (int m = 0; m < 4; ++m)
; #pragma unroll
;                     for (int n = 0; n < 2; ++n) acc[a][b][m][n] = (f32x4){0.f, 0.f, 0.f, 0.f};
;         cur = nxt; cA = nA; cB = nB; ++ui;
.LBB0_164:
	s_ashr_i32 s25, s24, 31
	s_lshl_b64 s[14:15], s[24:25], 19
	s_add_u32 s28, s26, s14
	s_addc_u32 s29, s27, s15
	s_and_b64 s[14:15], s[6:7], exec
	s_cselect_b32 s14, s29, s9
	s_cselect_b32 s15, s28, s8
	s_ashr_i32 s13, s12, 31
	s_lshl_b64 s[16:17], s[12:13], 19
	s_add_u32 s30, s23, s16
	s_addc_u32 s31, s35, s17
	s_and_b64 s[16:17], s[6:7], exec
	s_cselect_b32 s13, s31, s43
	s_cselect_b32 s25, s30, s42
	s_add_u32 s8, s8, 0x40080
	s_addc_u32 s9, s9, 0
	s_add_u32 s53, s42, 0x100
	v_mov_b32_e32 v8, 0
	s_addc_u32 s54, s43, 0
	s_mov_b32 s55, -2
	v_mov_b32_e32 v9, v8
	v_mov_b32_e32 v10, v8
	v_mov_b32_e32 v11, v8
	v_mov_b32_e32 v12, v8
	v_mov_b32_e32 v13, v8
	v_mov_b32_e32 v14, v8
	v_mov_b32_e32 v15, v8
	v_mov_b32_e32 v16, v8
	v_mov_b32_e32 v17, v8
	v_mov_b32_e32 v18, v8
	v_mov_b32_e32 v19, v8
	v_mov_b32_e32 v20, v8
	v_mov_b32_e32 v21, v8
	v_mov_b32_e32 v22, v8
	v_mov_b32_e32 v23, v8
	v_mov_b32_e32 v24, v8
	v_mov_b32_e32 v25, v8
	v_mov_b32_e32 v26, v8
	v_mov_b32_e32 v27, v8
	v_mov_b32_e32 v28, v8
	v_mov_b32_e32 v29, v8
	v_mov_b32_e32 v30, v8
	v_mov_b32_e32 v31, v8
	v_mov_b32_e32 v32, v8
	v_mov_b32_e32 v33, v8
	v_mov_b32_e32 v34, v8
	v_mov_b32_e32 v35, v8
	v_mov_b32_e32 v36, v8
	v_mov_b32_e32 v37, v8
	v_mov_b32_e32 v38, v8
	v_mov_b32_e32 v39, v8
	v_mov_b32_e32 v56, v8
	v_mov_b32_e32 v57, v8
	v_mov_b32_e32 v58, v8
	v_mov_b32_e32 v59, v8
	v_mov_b32_e32 v60, v8
	v_mov_b32_e32 v61, v8
	v_mov_b32_e32 v62, v8
	v_mov_b32_e32 v63, v8
	v_mov_b32_e32 v72, v8
	v_mov_b32_e32 v73, v8
	v_mov_b32_e32 v74, v8
	v_mov_b32_e32 v75, v8
	v_mov_b32_e32 v80, v8
	v_mov_b32_e32 v81, v8
	v_mov_b32_e32 v82, v8
	v_mov_b32_e32 v83, v8
	v_mov_b32_e32 v88, v8
	v_mov_b32_e32 v89, v8
	v_mov_b32_e32 v90, v8
	v_mov_b32_e32 v91, v8
	v_mov_b32_e32 v92, v8
	v_mov_b32_e32 v93, v8
	v_mov_b32_e32 v94, v8
	v_mov_b32_e32 v95, v8
	v_mov_b32_e32 v96, v8
	v_mov_b32_e32 v97, v8
	v_mov_b32_e32 v98, v8
	v_mov_b32_e32 v99, v8
	v_mov_b32_e32 v100, v8
	v_mov_b32_e32 v101, v8
	v_mov_b32_e32 v102, v8
	v_mov_b32_e32 v103, v8
	v_mov_b32_e32 v40, v8
	v_mov_b32_e32 v41, v8
	v_mov_b32_e32 v42, v8
	v_mov_b32_e32 v43, v8
	v_mov_b32_e32 v44, v8
	v_mov_b32_e32 v45, v8
	v_mov_b32_e32 v46, v8
	v_mov_b32_e32 v47, v8
	v_mov_b32_e32 v48, v8
	v_mov_b32_e32 v49, v8
	v_mov_b32_e32 v50, v8
	v_mov_b32_e32 v51, v8
	v_mov_b32_e32 v52, v8
	v_mov_b32_e32 v53, v8
	v_mov_b32_e32 v54, v8
	v_mov_b32_e32 v55, v8
	v_mov_b32_e32 v64, v8
	v_mov_b32_e32 v65, v8
	v_mov_b32_e32 v66, v8
	v_mov_b32_e32 v67, v8
	v_mov_b32_e32 v68, v8
	v_mov_b32_e32 v69, v8
	v_mov_b32_e32 v70, v8
	v_mov_b32_e32 v71, v8
	v_mov_b32_e32 v76, v8
	v_mov_b32_e32 v77, v8
	v_mov_b32_e32 v78, v8
	v_mov_b32_e32 v79, v8
	v_mov_b32_e32 v84, v8
	v_mov_b32_e32 v85, v8
	v_mov_b32_e32 v86, v8
	v_mov_b32_e32 v87, v8
	v_mov_b32_e32 v104, v8
	v_mov_b32_e32 v105, v8
	v_mov_b32_e32 v106, v8
	v_mov_b32_e32 v107, v8
	v_mov_b32_e32 v108, v8
	v_mov_b32_e32 v109, v8
	v_mov_b32_e32 v110, v8
	v_mov_b32_e32 v111, v8
	v_mov_b32_e32 v112, v8
	v_mov_b32_e32 v113, v8
	v_mov_b32_e32 v114, v8
	v_mov_b32_e32 v115, v8
	v_mov_b32_e32 v116, v8
	v_mov_b32_e32 v117, v8
	v_mov_b32_e32 v118, v8
	v_mov_b32_e32 v119, v8
	v_mov_b32_e32 v120, v8
	v_mov_b32_e32 v121, v8
	v_mov_b32_e32 v122, v8
	v_mov_b32_e32 v123, v8
	v_mov_b32_e32 v124, v8
	v_mov_b32_e32 v125, v8
	v_mov_b32_e32 v126, v8
	v_mov_b32_e32 v127, v8
	v_mov_b32_e32 v128, v8
	v_mov_b32_e32 v129, v8
	v_mov_b32_e32 v130, v8
	v_mov_b32_e32 v131, v8
	v_mov_b32_e32 v132, v8
	v_mov_b32_e32 v133, v8
	v_mov_b32_e32 v134, v8
	v_mov_b32_e32 v135, v8
	s_add_u32 s16, s8, 0xfffc0080
	s_addc_u32 s17, s9, -1
	s_cmp_eq_u32 s55, 12
	s_cselect_b32 s43, s14, s17
	s_cselect_b32 s42, s15, s16
	s_cselect_b32 s41, s13, s54
	s_cselect_b32 s40, s25, s53
.LBB0_165:
	s_add_i32 s18, 0, 0x10000
	v_add_u32_e32 v0, s18, v194
	s_add_i32 s19, 0, 0x14000
	ds_read_b128 v[136:139], v0
	ds_read_b128 v[140:143], v0 offset:1024
	ds_read_b128 v[144:147], v0 offset:2048
	ds_read_b128 v[148:151], v0 offset:3072
	v_add_u32_e32 v0, s19, v194
	ds_read_b128 v[152:155], v0
	ds_read_b128 v[186:189], v0 offset:1024
	ds_read_b128 v[190:193], v0 offset:2048
	ds_read_b128 v[198:201], v0 offset:3072
	v_lshl_add_u64 v[2:3], s[8:9], 0, v[182:183]
	s_add_i32 m0, s45, 0xc000
	ds_read_b128 v[210:213], v196
	ds_read_b128 v[214:217], v196 offset:1024
	ds_read_b128 v[218:221], v196 offset:2048
	ds_read_b128 v[222:225], v196 offset:3072
	ds_read_b128 v[226:229], v196 offset:4096
	ds_read_b128 v[230:233], v196 offset:5120
	ds_read_b128 v[234:237], v196 offset:6144
	ds_read_b128 v[238:241], v196 offset:7168
	global_load_lds_dwordx4 v[2:3], off
	v_lshl_add_u64 v[2:3], s[8:9], 0, v[184:185]
	s_add_i32 m0, s45, 0xe000
	s_nop 0
	global_load_lds_dwordx4 v[2:3], off
	s_waitcnt vmcnt(8)
	s_waitcnt lgkmcnt(0)
	s_barrier
; #define PG8_STAGE(bufoff, gbase, voff) do { _Pragma("unroll") for (int _i = 0; _i < 2; ++_i) \
;         __builtin_amdgcn_global_load_lds((const unsigned*)((const char*)(gbase) + (voff)[_i]), (PG8_LAS unsigned*)(lds + (bufoff) + ldsw + _i * 8192), 16, 0, 0); } while (0)
; #define PG8_LDA(dst, b, h) do { _Pragma("unroll") for (int m = 0; m < 4; ++m) _Pragma("unroll") for (int k = 0; k < 2; ++k) dst[m][k] = *(const PG8_LAS bf16x8*)(lds + PG8_SA(b, h) + aoff + m * 2048 + k * 1024); } while (0)
; #define PG8_MMA(ai, bj, At, Bt) do { __builtin_amdgcn_s_setprio(1); _Pragma("unroll") for (int m = 0; m < 4; ++m) _Pragma("unroll") for (int n = 0; n < 2; ++n) _Pragma("unroll") for (int k = 0; k < 2; ++k) \
;         acc[ai][bj][m][n] = __builtin_amdgcn_mfma_f32_16x16x32_bf16(Bt[n][k], At[m][k], acc[ai][bj][m][n], 0, 0, 0); __builtin_amdgcn_s_setprio(0); } while (0)
; #define PG8_WAIT_V(n) asm volatile("s_waitcnt vmcnt(" #n ")" ::: "memory")
; #define PG8_WAIT_L(n) asm volatile("s_waitcnt lgkmcnt(" #n ")" ::: "memory")
; #define PG8_BAR __builtin_amdgcn_s_barrier()
; #define PG8_SCHED __builtin_amdgcn_sched_barrier(0)
; template <class Epi, class Sched, bool ALIGN_EPI = false, bool SP2 = false>
; __device__ __forceinline__ void gemm_phase(PG8_LAS unsigned char* lds, const Gemm g, const Sched& S, const Epi& E) {
;     ...
;             PG8_WAIT_V(8); PG8_WAIT_L(0); PG8_BAR; PG8_MMA(0, 0, At, B0); PG8_MMA(0, 1, At, B1); PG8_BAR; PG8_SCHED;
;             PG8_LDA(At, 0, 1); PG8_STAGE(PG8_SB(0, 0), b2, voffB); PG8_STAGE(PG8_SB(0, 1), b2 + hstep, voffB); PG8_STAGE(PG8_SA(0, 0), a2, voffA);
;             PG8_WAIT_V(8); PG8_WAIT_L(0); PG8_BAR; PG8_MMA(1, 0, At, B0); PG8_MMA(1, 1, At, B1); PG8_BAR; PG8_SCHED;
	s_waitcnt lgkmcnt(0)
	v_mfma_f32_16x16x32_bf16 v[132:135], v[136:139], v[210:213], v[132:135]
	v_mfma_f32_16x16x32_bf16 v[128:131], v[144:147], v[210:213], v[128:131]
	v_mfma_f32_16x16x32_bf16 v[124:127], v[136:139], v[218:221], v[124:127]
	v_mfma_f32_16x16x32_bf16 v[120:123], v[144:147], v[218:221], v[120:123]
	s_setprio 1
	v_mfma_f32_16x16x32_bf16 v[116:119], v[136:139], v[226:229], v[116:119]
	v_mfma_f32_16x16x32_bf16 v[112:115], v[144:147], v[226:229], v[112:115]
	v_mfma_f32_16x16x32_bf16 v[108:111], v[136:139], v[234:237], v[108:111]
	v_mfma_f32_16x16x32_bf16 v[104:107], v[144:147], v[234:237], v[104:107]
	v_mfma_f32_16x16x32_bf16 v[132:135], v[140:143], v[214:217], v[132:135]
	v_mfma_f32_16x16x32_bf16 v[128:131], v[148:151], v[214:217], v[128:131]
	v_mfma_f32_16x16x32_bf16 v[124:127], v[140:143], v[222:225], v[124:127]
	v_mfma_f32_16x16x32_bf16 v[120:123], v[148:151], v[222:225], v[120:123]
	v_mfma_f32_16x16x32_bf16 v[116:119], v[140:143], v[230:233], v[116:119]
	v_mfma_f32_16x16x32_bf16 v[112:115], v[148:151], v[230:233], v[112:115]
	v_mfma_f32_16x16x32_bf16 v[108:111], v[140:143], v[238:241], v[108:111]
	v_mfma_f32_16x16x32_bf16 v[104:107], v[148:151], v[238:241], v[104:107]
	s_setprio 0
	s_setprio 1
	v_mfma_f32_16x16x32_bf16 v[84:87], v[152:155], v[210:213], v[84:87]
	v_mfma_f32_16x16x32_bf16 v[76:79], v[190:193], v[210:213], v[76:79]
	v_mfma_f32_16x16x32_bf16 v[68:71], v[152:155], v[218:221], v[68:71]
	v_mfma_f32_16x16x32_bf16 v[64:67], v[190:193], v[218:221], v[64:67]
	v_mfma_f32_16x16x32_bf16 v[52:55], v[152:155], v[226:229], v[52:55]
	v_mfma_f32_16x16x32_bf16 v[48:51], v[190:193], v[226:229], v[48:51]
	v_mfma_f32_16x16x32_bf16 v[44:47], v[152:155], v[234:237], v[44:47]
	v_mfma_f32_16x16x32_bf16 v[40:43], v[190:193], v[234:237], v[40:43]
	v_mfma_f32_16x16x32_bf16 v[84:87], v[186:189], v[214:217], v[84:87]
	v_mfma_f32_16x16x32_bf16 v[76:79], v[198:201], v[214:217], v[76:79]
	v_mfma_f32_16x16x32_bf16 v[68:71], v[186:189], v[222:225], v[68:71]
	v_mfma_f32_16x16x32_bf16 v[64:67], v[198:201], v[222:225], v[64:67]
	s_barrier
	v_mfma_f32_16x16x32_bf16 v[52:55], v[186:189], v[230:233], v[52:55]
	v_mfma_f32_16x16x32_bf16 v[48:51], v[198:201], v[230:233], v[48:51]
	v_mfma_f32_16x16x32_bf16 v[44:47], v[186:189], v[238:241], v[44:47]
	v_mfma_f32_16x16x32_bf16 v[40:43], v[198:201], v[238:241], v[40:43]
	s_setprio 0
	s_add_i32 s16, s18, s44
	v_lshl_add_u64 v[2:3], s[40:41], 0, v[162:163]
	s_mov_b32 m0, s16
	ds_read_b128 v[210:213], v196 offset:16384
	ds_read_b128 v[214:217], v196 offset:17408
	ds_read_b128 v[218:221], v196 offset:18432
	ds_read_b128 v[222:225], v196 offset:19456
	ds_read_b128 v[226:229], v196 offset:20480
	ds_read_b128 v[230:233], v196 offset:21504
	ds_read_b128 v[234:237], v196 offset:22528
	ds_read_b128 v[238:241], v196 offset:23552
	global_load_lds_dwordx4 v[2:3], off
	s_add_i32 m0, s16, 0x2000
	s_add_u32 s16, s40, 0x40000
	v_lshl_add_u64 v[156:157], s[40:41], 0, v[158:159]
	s_addc_u32 s17, s41, 0
	s_add_i32 s18, s19, s44
	global_load_lds_dwordx4 v[156:157], off
	v_lshl_add_u64 v[242:243], s[16:17], 0, v[162:163]
	s_mov_b32 m0, s18
	v_lshl_add_u64 v[244:245], s[42:43], 0, v[160:161]
	global_load_lds_dwordx4 v[242:243], off
	v_lshl_add_u64 v[242:243], s[16:17], 0, v[158:159]
	s_add_i32 m0, s18, 0x2000
	s_nop 0
	global_load_lds_dwordx4 v[242:243], off
	v_lshl_add_u64 v[242:243], s[42:43], 0, v[178:179]
	s_waitcnt vmcnt(6)
	s_waitcnt lgkmcnt(0)
	s_barrier
	s_waitcnt lgkmcnt(0)
	v_mfma_f32_16x16x32_bf16 v[100:103], v[136:139], v[210:213], v[100:103]
	v_mfma_f32_16x16x32_bf16 v[96:99], v[144:147], v[210:213], v[96:99]
	v_mfma_f32_16x16x32_bf16 v[92:95], v[136:139], v[218:221], v[92:95]
	s_mov_b32 m0, s45
	v_mfma_f32_16x16x32_bf16 v[88:91], v[144:147], v[218:221], v[88:91]
	s_setprio 1
	global_load_lds_dwordx4 v[242:243], off
	v_mfma_f32_16x16x32_bf16 v[80:83], v[136:139], v[226:229], v[80:83]
	v_mfma_f32_16x16x32_bf16 v[72:75], v[144:147], v[226:229], v[72:75]
	v_mfma_f32_16x16x32_bf16 v[60:63], v[136:139], v[234:237], v[60:63]
	v_mfma_f32_16x16x32_bf16 v[56:59], v[144:147], v[234:237], v[56:59]
	v_mfma_f32_16x16x32_bf16 v[100:103], v[140:143], v[214:217], v[100:103]
	v_mfma_f32_16x16x32_bf16 v[96:99], v[148:151], v[214:217], v[96:99]
	v_mfma_f32_16x16x32_bf16 v[92:95], v[140:143], v[222:225], v[92:95]
	s_mov_b32 m0, s46
	v_mfma_f32_16x16x32_bf16 v[88:91], v[148:151], v[222:225], v[88:91]
	global_load_lds_dwordx4 v[244:245], off
	v_mfma_f32_16x16x32_bf16 v[80:83], v[140:143], v[230:233], v[80:83]
	v_mfma_f32_16x16x32_bf16 v[72:75], v[148:151], v[230:233], v[72:75]
	v_mfma_f32_16x16x32_bf16 v[60:63], v[140:143], v[238:241], v[60:63]
	v_mfma_f32_16x16x32_bf16 v[56:59], v[148:151], v[238:241], v[56:59]
	s_setprio 0
	s_setprio 1
	v_mfma_f32_16x16x32_bf16 v[36:39], v[152:155], v[210:213], v[36:39]
	v_mfma_f32_16x16x32_bf16 v[32:35], v[190:193], v[210:213], v[32:35]
	v_mfma_f32_16x16x32_bf16 v[28:31], v[152:155], v[218:221], v[28:31]
	v_mfma_f32_16x16x32_bf16 v[24:27], v[190:193], v[218:221], v[24:27]
	v_mfma_f32_16x16x32_bf16 v[20:23], v[152:155], v[226:229], v[20:23]
	v_mfma_f32_16x16x32_bf16 v[16:19], v[190:193], v[226:229], v[16:19]
	v_mfma_f32_16x16x32_bf16 v[12:15], v[152:155], v[234:237], v[12:15]
	v_mfma_f32_16x16x32_bf16 v[8:11], v[190:193], v[234:237], v[8:11]
	v_mfma_f32_16x16x32_bf16 v[36:39], v[186:189], v[214:217], v[36:39]
	v_mfma_f32_16x16x32_bf16 v[32:35], v[198:201], v[214:217], v[32:35]
	v_mfma_f32_16x16x32_bf16 v[28:31], v[186:189], v[222:225], v[28:31]
	v_mfma_f32_16x16x32_bf16 v[24:27], v[198:201], v[222:225], v[24:27]
	s_barrier
; #define PG8_STAGE(bufoff, gbase, voff) do { _Pragma("unroll") for (int _i = 0; _i < 2; ++_i) \
;         __builtin_amdgcn_global_load_lds((const unsigned*)((const char*)(gbase) + (voff)[_i]), (PG8_LAS unsigned*)(lds + (bufoff) + ldsw + _i * 8192), 16, 0, 0); } while (0)
; #define PG8_LDA(dst, b, h) do { _Pragma("unroll") for (int m = 0; m < 4; ++m) _Pragma("unroll") for (int k = 0; k < 2; ++k) dst[m][k] = *(const PG8_LAS bf16x8*)(lds + PG8_SA(b, h) + aoff + m * 2048 + k * 1024); } while (0)
; #define PG8_LDB(dst, b, h) do { _Pragma("unroll") for (int n = 0; n < 2; ++n) _Pragma("unroll") for (int k = 0; k < 2; ++k) dst[n][k] = *(const PG8_LAS bf16x8*)(lds + PG8_SB(b, h) + boff + n * 2048 + k * 1024); } while (0)
; #define PG8_MMA(ai, bj, At, Bt) do { __builtin_amdgcn_s_setprio(1); _Pragma("unroll") for (int m = 0; m < 4; ++m) _Pragma("unroll") for (int n = 0; n < 2; ++n) _Pragma("unroll") for (int k = 0; k < 2; ++k) \
;         acc[ai][bj][m][n] = __builtin_amdgcn_mfma_f32_16x16x32_bf16(Bt[n][k], At[m][k], acc[ai][bj][m][n], 0, 0, 0); __builtin_amdgcn_s_setprio(0); } while (0)
; #define PG8_WAIT_V(n) asm volatile("s_waitcnt vmcnt(" #n ")" ::: "memory")
; #define PG8_WAIT_L(n) asm volatile("s_waitcnt lgkmcnt(" #n ")" ::: "memory")
; #define PG8_BAR __builtin_amdgcn_s_barrier()
; #define PG8_SCHED __builtin_amdgcn_sched_barrier(0)
; template <class Epi, class Sched, bool ALIGN_EPI = false, bool SP2 = false>
; __device__ __forceinline__ void gemm_phase(PG8_LAS unsigned char* lds, const Gemm g, const Sched& S, const Epi& E) {
;     ...
;             PG8_LDB(B0, 1, 0); PG8_LDB(B1, 1, 1); PG8_SCHED; PG8_LDA(At, 1, 0); PG8_STAGE(PG8_SA(0, 1), a2 + hstep, voffA);
;             PG8_WAIT_V(8); PG8_WAIT_L(0); PG8_BAR; PG8_MMA(0, 0, At, B0); PG8_MMA(0, 1, At, B1); PG8_BAR; PG8_SCHED;
	v_mfma_f32_16x16x32_bf16 v[20:23], v[186:189], v[230:233], v[20:23]
	v_mfma_f32_16x16x32_bf16 v[16:19], v[198:201], v[230:233], v[16:19]
	v_mfma_f32_16x16x32_bf16 v[12:15], v[186:189], v[238:241], v[12:15]
	v_mfma_f32_16x16x32_bf16 v[8:11], v[198:201], v[238:241], v[8:11]
	s_setprio 0
	s_add_i32 s18, 0, 0x18000
	v_add_u32_e32 v0, s18, v194
	ds_read_b128 v[136:139], v0
	ds_read_b128 v[140:143], v0 offset:1024
	ds_read_b128 v[144:147], v0 offset:2048
	ds_read_b128 v[148:151], v0 offset:3072
	v_add_u32_e32 v0, s33, v194
	ds_read_b128 v[152:155], v0
	ds_read_b128 v[186:189], v0 offset:1024
	ds_read_b128 v[190:193], v0 offset:2048
	ds_read_b128 v[198:201], v0 offset:3072
	s_add_u32 s16, s42, 0x40000
	s_addc_u32 s17, s43, 0
	s_mov_b32 m0, s47
	v_lshl_add_u64 v[246:247], s[16:17], 0, v[178:179]
	ds_read_b128 v[210:213], v196 offset:32768
	ds_read_b128 v[214:217], v196 offset:33792
	ds_read_b128 v[218:221], v196 offset:34816
	ds_read_b128 v[222:225], v196 offset:35840
	ds_read_b128 v[226:229], v196 offset:36864
	ds_read_b128 v[230:233], v196 offset:37888
	ds_read_b128 v[234:237], v196 offset:38912
	ds_read_b128 v[238:241], v196 offset:39936
	global_load_lds_dwordx4 v[246:247], off
	v_lshl_add_u64 v[246:247], s[16:17], 0, v[160:161]
	s_mov_b32 m0, s48
	s_nop 0
	global_load_lds_dwordx4 v[246:247], off
	s_waitcnt vmcnt(8)
	s_waitcnt lgkmcnt(0)
	s_barrier
	s_waitcnt lgkmcnt(0)
	v_mfma_f32_16x16x32_bf16 v[132:135], v[136:139], v[210:213], v[132:135]
	v_mfma_f32_16x16x32_bf16 v[128:131], v[144:147], v[210:213], v[128:131]
	v_mfma_f32_16x16x32_bf16 v[124:127], v[136:139], v[218:221], v[124:127]
	v_mfma_f32_16x16x32_bf16 v[120:123], v[144:147], v[218:221], v[120:123]
	s_setprio 1
	v_mfma_f32_16x16x32_bf16 v[116:119], v[136:139], v[226:229], v[116:119]
	v_mfma_f32_16x16x32_bf16 v[112:115], v[144:147], v[226:229], v[112:115]
	v_mfma_f32_16x16x32_bf16 v[108:111], v[136:139], v[234:237], v[108:111]
	v_mfma_f32_16x16x32_bf16 v[104:107], v[144:147], v[234:237], v[104:107]
	v_mfma_f32_16x16x32_bf16 v[132:135], v[140:143], v[214:217], v[132:135]
	v_mfma_f32_16x16x32_bf16 v[128:131], v[148:151], v[214:217], v[128:131]
	v_mfma_f32_16x16x32_bf16 v[124:127], v[140:143], v[222:225], v[124:127]
	v_mfma_f32_16x16x32_bf16 v[120:123], v[148:151], v[222:225], v[120:123]
	v_mfma_f32_16x16x32_bf16 v[116:119], v[140:143], v[230:233], v[116:119]
	v_mfma_f32_16x16x32_bf16 v[112:115], v[148:151], v[230:233], v[112:115]
	v_mfma_f32_16x16x32_bf16 v[108:111], v[140:143], v[238:241], v[108:111]
	v_mfma_f32_16x16x32_bf16 v[104:107], v[148:151], v[238:241], v[104:107]
	s_setprio 0
	s_setprio 1
	v_mfma_f32_16x16x32_bf16 v[84:87], v[152:155], v[210:213], v[84:87]
	v_mfma_f32_16x16x32_bf16 v[76:79], v[190:193], v[210:213], v[76:79]
	v_mfma_f32_16x16x32_bf16 v[68:71], v[152:155], v[218:221], v[68:71]
	v_mfma_f32_16x16x32_bf16 v[64:67], v[190:193], v[218:221], v[64:67]
	v_mfma_f32_16x16x32_bf16 v[52:55], v[152:155], v[226:229], v[52:55]
	v_mfma_f32_16x16x32_bf16 v[48:51], v[190:193], v[226:229], v[48:51]
	v_mfma_f32_16x16x32_bf16 v[44:47], v[152:155], v[234:237], v[44:47]
	v_mfma_f32_16x16x32_bf16 v[40:43], v[190:193], v[234:237], v[40:43]
	v_mfma_f32_16x16x32_bf16 v[84:87], v[186:189], v[214:217], v[84:87]
	v_mfma_f32_16x16x32_bf16 v[76:79], v[198:201], v[214:217], v[76:79]
	v_mfma_f32_16x16x32_bf16 v[68:71], v[186:189], v[222:225], v[68:71]
	v_mfma_f32_16x16x32_bf16 v[64:67], v[198:201], v[222:225], v[64:67]
	s_barrier
; #define PG8_STAGE(bufoff, gbase, voff) do { _Pragma("unroll") for (int _i = 0; _i < 2; ++_i) \
;         __builtin_amdgcn_global_load_lds((const unsigned*)((const char*)(gbase) + (voff)[_i]), (PG8_LAS unsigned*)(lds + (bufoff) + ldsw + _i * 8192), 16, 0, 0); } while (0)
; #define PG8_LDA(dst, b, h) do { _Pragma("unroll") for (int m = 0; m < 4; ++m) _Pragma("unroll") for (int k = 0; k < 2; ++k) dst[m][k] = *(const PG8_LAS bf16x8*)(lds + PG8_SA(b, h) + aoff + m * 2048 + k * 1024); } while (0)
; #define PG8_MMA(ai, bj, At, Bt) do { __builtin_amdgcn_s_setprio(1); _Pragma("unroll") for (int m = 0; m < 4; ++m) _Pragma("unroll") for (int n = 0; n < 2; ++n) _Pragma("unroll") for (int k = 0; k < 2; ++k) \
;         acc[ai][bj][m][n] = __builtin_amdgcn_mfma_f32_16x16x32_bf16(Bt[n][k], At[m][k], acc[ai][bj][m][n], 0, 0, 0); __builtin_amdgcn_s_setprio(0); } while (0)
; #define PG8_WAIT_V(n) asm volatile("s_waitcnt vmcnt(" #n ")" ::: "memory")
; #define PG8_WAIT_L(n) asm volatile("s_waitcnt lgkmcnt(" #n ")" ::: "memory")
; #define PG8_BAR __builtin_amdgcn_s_barrier()
; #define PG8_SCHED __builtin_amdgcn_sched_barrier(0)
; template <class Epi, class Sched, bool ALIGN_EPI = false, bool SP2 = false>
; __device__ __forceinline__ void gemm_phase(PG8_LAS unsigned char* lds, const Gemm g, const Sched& S, const Epi& E) {
;     ...
;         for (int t = 0; t < nt; t += 2) {
;             const bool last = (t == nt - 2);
;             const char* a1 = cA + (size_t)(t + 1) * kstep;
;             const char* a2 = last ? nA : cA + (size_t)(t + 2) * kstep; const char* b2 = last ? nB : cB + (size_t)(t + 2) * kstep;
;             const char* a3 = a2 + kstep; const char* b3 = b2 + kstep;
;     ...
;             PG8_LDA(At, 1, 1); PG8_STAGE(PG8_SB(1, 0), b3, voffB); PG8_STAGE(PG8_SB(1, 1), b3 + hstep, voffB); PG8_STAGE(PG8_SA(1, 0), a3, voffA);
;             PG8_WAIT_V(8); PG8_WAIT_L(0); PG8_BAR; PG8_MMA(1, 0, At, B0); PG8_MMA(1, 1, At, B1); PG8_BAR; PG8_SCHED;
	v_mfma_f32_16x16x32_bf16 v[52:55], v[186:189], v[230:233], v[52:55]
	v_mfma_f32_16x16x32_bf16 v[48:51], v[198:201], v[230:233], v[48:51]
	v_mfma_f32_16x16x32_bf16 v[44:47], v[186:189], v[238:241], v[44:47]
	v_mfma_f32_16x16x32_bf16 v[40:43], v[198:201], v[238:241], v[40:43]
	s_setprio 0
	s_add_i32 s16, s18, s44
	v_lshl_add_u64 v[2:3], v[2:3], 0, s[20:21]
	s_mov_b32 m0, s16
	ds_read_b128 v[210:213], v196 offset:49152
	ds_read_b128 v[214:217], v196 offset:50176
	ds_read_b128 v[218:221], v196 offset:51200
	ds_read_b128 v[222:225], v196 offset:52224
	ds_read_b128 v[226:229], v196 offset:53248
	ds_read_b128 v[230:233], v196 offset:54272
	ds_read_b128 v[234:237], v196 offset:55296
	ds_read_b128 v[238:241], v196 offset:56320
	global_load_lds_dwordx4 v[2:3], off
	s_add_i32 m0, s16, 0x2000
	s_add_u32 s16, s40, 0x40080
	v_lshl_add_u64 v[2:3], v[156:157], 0, s[20:21]
	s_addc_u32 s17, s41, 0
	s_add_i32 s18, s33, s44
	global_load_lds_dwordx4 v[2:3], off
	v_lshl_add_u64 v[2:3], s[16:17], 0, v[162:163]
	s_mov_b32 m0, s18
	s_nop 0
	global_load_lds_dwordx4 v[2:3], off
	v_lshl_add_u64 v[2:3], s[16:17], 0, v[158:159]
	s_add_i32 m0, s18, 0x2000
	s_nop 0
	global_load_lds_dwordx4 v[2:3], off
	v_lshl_add_u64 v[2:3], v[242:243], 0, s[20:21]
	v_lshl_add_u64 v[244:245], v[244:245], 0, s[20:21]
	s_waitcnt vmcnt(6)
	s_waitcnt lgkmcnt(0)
	s_barrier
	s_waitcnt lgkmcnt(0)
	v_mfma_f32_16x16x32_bf16 v[100:103], v[136:139], v[210:213], v[100:103]
	v_mfma_f32_16x16x32_bf16 v[96:99], v[144:147], v[210:213], v[96:99]
	v_mfma_f32_16x16x32_bf16 v[92:95], v[136:139], v[218:221], v[92:95]
	s_mov_b32 m0, s49
	v_mfma_f32_16x16x32_bf16 v[88:91], v[144:147], v[218:221], v[88:91]
	s_setprio 1
	global_load_lds_dwordx4 v[2:3], off
	v_mfma_f32_16x16x32_bf16 v[80:83], v[136:139], v[226:229], v[80:83]
	v_mfma_f32_16x16x32_bf16 v[72:75], v[144:147], v[226:229], v[72:75]
	v_mfma_f32_16x16x32_bf16 v[60:63], v[136:139], v[234:237], v[60:63]
	s_add_i32 s55, s55, 2
	v_mfma_f32_16x16x32_bf16 v[56:59], v[144:147], v[234:237], v[56:59]
	s_add_u32 s8, s8, 0x100
	s_addc_u32 s9, s9, 0
	v_mfma_f32_16x16x32_bf16 v[100:103], v[140:143], v[214:217], v[100:103]
	s_add_u32 s53, s53, 0x100
	s_addc_u32 s54, s54, 0
	v_mfma_f32_16x16x32_bf16 v[96:99], v[148:151], v[214:217], v[96:99]
	s_add_u32 s16, s8, 0xfffc0080
	s_addc_u32 s17, s9, -1
	v_mfma_f32_16x16x32_bf16 v[92:95], v[140:143], v[222:225], v[92:95]
	s_cmp_eq_u32 s55, 12
	s_cselect_b32 s43, s14, s17
	s_cselect_b32 s42, s15, s16
	s_mov_b32 m0, s50
	v_mfma_f32_16x16x32_bf16 v[88:91], v[148:151], v[222:225], v[88:91]
	s_cselect_b32 s41, s13, s54
	s_cselect_b32 s40, s25, s53
	global_load_lds_dwordx4 v[244:245], off
	v_mfma_f32_16x16x32_bf16 v[80:83], v[140:143], v[230:233], v[80:83]
	v_mfma_f32_16x16x32_bf16 v[72:75], v[148:151], v[230:233], v[72:75]
	v_mfma_f32_16x16x32_bf16 v[60:63], v[140:143], v[238:241], v[60:63]
	v_mfma_f32_16x16x32_bf16 v[56:59], v[148:151], v[238:241], v[56:59]
	s_setprio 0
	s_setprio 1
	v_mfma_f32_16x16x32_bf16 v[36:39], v[152:155], v[210:213], v[36:39]
	v_mfma_f32_16x16x32_bf16 v[32:35], v[190:193], v[210:213], v[32:35]
	v_mfma_f32_16x16x32_bf16 v[28:31], v[152:155], v[218:221], v[28:31]
	v_mfma_f32_16x16x32_bf16 v[24:27], v[190:193], v[218:221], v[24:27]
	v_mfma_f32_16x16x32_bf16 v[20:23], v[152:155], v[226:229], v[20:23]
	v_mfma_f32_16x16x32_bf16 v[16:19], v[190:193], v[226:229], v[16:19]
	v_mfma_f32_16x16x32_bf16 v[12:15], v[152:155], v[234:237], v[12:15]
	v_mfma_f32_16x16x32_bf16 v[8:11], v[190:193], v[234:237], v[8:11]
	v_mfma_f32_16x16x32_bf16 v[36:39], v[186:189], v[214:217], v[36:39]
	v_mfma_f32_16x16x32_bf16 v[32:35], v[198:201], v[214:217], v[32:35]
	v_mfma_f32_16x16x32_bf16 v[28:31], v[186:189], v[222:225], v[28:31]
	v_mfma_f32_16x16x32_bf16 v[24:27], v[198:201], v[222:225], v[24:27]
	s_barrier
	v_mfma_f32_16x16x32_bf16 v[20:23], v[186:189], v[230:233], v[20:23]
	v_mfma_f32_16x16x32_bf16 v[16:19], v[198:201], v[230:233], v[16:19]
	v_mfma_f32_16x16x32_bf16 v[12:15], v[186:189], v[238:241], v[12:15]
	v_mfma_f32_16x16x32_bf16 v[8:11], v[198:201], v[238:241], v[8:11]
	s_setprio 0
	s_cmp_gt_u32 s55, 13
	s_cbranch_scc0 .LBB0_165
	s_and_b64 vcc, exec, s[10:11]
	s_cbranch_vccz .LBB0_168
	s_barrier
	s_setprio 1

; #define PG8_STAGE(bufoff, gbase, voff) do { _Pragma("unroll") for (int _i = 0; _i < 2; ++_i) \
;         __builtin_amdgcn_global_load_lds((const unsigned*)((const char*)(gbase) + (voff)[_i]), (PG8_LAS unsigned*)(lds + (bufoff) + ldsw + _i * 8192), 16, 0, 0); } while (0)
; #define PG8_LDA(dst, b, h) do { _Pragma("unroll") for (int m = 0; m < 4; ++m) _Pragma("unroll") for (int k = 0; k < 2; ++k) dst[m][k] = *(const PG8_LAS bf16x8*)(lds + PG8_SA(b, h) + aoff + m * 2048 + k * 1024); } while (0)
; #define PG8_LDB(dst, b, h) do { _Pragma("unroll") for (int n = 0; n < 2; ++n) _Pragma("unroll") for (int k = 0; k < 2; ++k) dst[n][k] = *(const PG8_LAS bf16x8*)(lds + PG8_SB(b, h) + boff + n * 2048 + k * 1024); } while (0)
; #define PG8_WAIT_V(n) asm volatile("s_waitcnt vmcnt(" #n ")" ::: "memory")
; #define PG8_WAIT_L(n) asm volatile("s_waitcnt lgkmcnt(" #n ")" ::: "memory")
; #define PG8_BAR __builtin_amdgcn_s_barrier()
; template <class Epi, class Sched, bool ALIGN_EPI = false, bool SP2 = false>
; __device__ __forceinline__ void gemm_phase(PG8_LAS unsigned char* lds, const Gemm g, const Sched& S, const Epi& E) {
;     ...
;     for (;;) {
;         const bool has_next = S.next(ui + 1, nxt);
;         const char* nA = has_next ? (const char*)g.A + (size_t)nxt.pm * tstep : cA; const char* nB = has_next ? (const char*)g.Bt + (size_t)nxt.pn * tstep : cB;
;         for (int t = 0; t < nt; t += 2) {
;             const bool last = (t == nt - 2);
;             const char* a1 = cA + (size_t)(t + 1) * kstep;
;             const char* a2 = last ? nA : cA + (size_t)(t + 2) * kstep; const char* b2 = last ? nB : cB + (size_t)(t + 2) * kstep;
;             const char* a3 = a2 + kstep; const char* b3 = b2 + kstep;
;             if (last && has_next) S.a_ready(nxt);
;             if constexpr (SP2) {
;             PG8_LDB(B0, 0, 0); PG8_LDB(B1, 0, 1); PG8_SCHED; PG8_LDA(At, 0, 0); PG8_STAGE(PG8_SA(1, 1), a1 + hstep, voffA);
;             PG8_WAIT_V(8); PG8_WAIT_L(0); PG8_BAR; PG8_MMA(0, 0, At, B0); PG8_MMA(0, 1, At, B1); PG8_BAR; PG8_SCHED;
;     ...
; #pragma unroll
;         for (int a = 0; a < 2; ++a)
; #pragma unroll
;             for (int b = 0; b < 2; ++b)
; #pragma unroll
;                 for (int m = 0; m < 4; ++m)
; #pragma unroll
;                     for (int n = 0; n < 2; ++n) acc[a][b][m][n] = (f32x4){0.f, 0.f, 0.f, 0.f};
;         cur = nxt; cA = nA; cB = nB; ++ui;
.LBB0_256:
	s_ashr_i32 s25, s24, 31
	s_lshl_b64 s[14:15], s[24:25], 19
	s_add_u32 s28, s26, s14
	s_addc_u32 s29, s27, s15
	s_and_b64 s[14:15], s[6:7], exec
	s_cselect_b32 s14, s29, s9
	s_cselect_b32 s15, s28, s8
	s_ashr_i32 s13, s12, 31
	s_lshl_b64 s[16:17], s[12:13], 19
	s_add_u32 s30, s23, s16
	s_addc_u32 s31, s35, s17
	s_and_b64 s[16:17], s[6:7], exec
	s_cselect_b32 s13, s31, s41
	s_cselect_b32 s25, s30, s40
	s_add_u32 s8, s8, 0x40080
	s_addc_u32 s9, s9, 0
	s_add_u32 s53, s40, 0x100
	v_mov_b32_e32 v8, 0
	s_addc_u32 s54, s41, 0
	s_mov_b32 s55, -2
	v_mov_b32_e32 v9, v8
	v_mov_b32_e32 v10, v8
	v_mov_b32_e32 v11, v8
	v_mov_b32_e32 v16, v8
	v_mov_b32_e32 v17, v8
	v_mov_b32_e32 v18, v8
	v_mov_b32_e32 v19, v8
	v_mov_b32_e32 v24, v8
	v_mov_b32_e32 v25, v8
	v_mov_b32_e32 v26, v8
	v_mov_b32_e32 v27, v8
	v_mov_b32_e32 v32, v8
	v_mov_b32_e32 v33, v8
	v_mov_b32_e32 v34, v8
	v_mov_b32_e32 v35, v8
	v_mov_b32_e32 v40, v8
	v_mov_b32_e32 v41, v8
	v_mov_b32_e32 v42, v8
	v_mov_b32_e32 v43, v8
	v_mov_b32_e32 v48, v8
	v_mov_b32_e32 v49, v8
	v_mov_b32_e32 v50, v8
	v_mov_b32_e32 v51, v8
	v_mov_b32_e32 v56, v8
	v_mov_b32_e32 v57, v8
	v_mov_b32_e32 v58, v8
	v_mov_b32_e32 v59, v8
	v_mov_b32_e32 v64, v8
	v_mov_b32_e32 v65, v8
	v_mov_b32_e32 v66, v8
	v_mov_b32_e32 v67, v8
	v_mov_b32_e32 v12, v8
	v_mov_b32_e32 v13, v8
	v_mov_b32_e32 v14, v8
	v_mov_b32_e32 v15, v8
	v_mov_b32_e32 v20, v8
	v_mov_b32_e32 v21, v8
	v_mov_b32_e32 v22, v8
	v_mov_b32_e32 v23, v8
	v_mov_b32_e32 v28, v8
	v_mov_b32_e32 v29, v8
	v_mov_b32_e32 v30, v8
	v_mov_b32_e32 v31, v8
	v_mov_b32_e32 v36, v8
	v_mov_b32_e32 v37, v8
	v_mov_b32_e32 v38, v8
	v_mov_b32_e32 v39, v8
	v_mov_b32_e32 v44, v8
	v_mov_b32_e32 v45, v8
	v_mov_b32_e32 v46, v8
	v_mov_b32_e32 v47, v8
	v_mov_b32_e32 v52, v8
	v_mov_b32_e32 v53, v8
	v_mov_b32_e32 v54, v8
	v_mov_b32_e32 v55, v8
	v_mov_b32_e32 v60, v8
	v_mov_b32_e32 v61, v8
	v_mov_b32_e32 v62, v8
	v_mov_b32_e32 v63, v8
	v_mov_b32_e32 v68, v8
	v_mov_b32_e32 v69, v8
	v_mov_b32_e32 v70, v8
	v_mov_b32_e32 v71, v8
	v_mov_b32_e32 v72, v8
	v_mov_b32_e32 v73, v8
	v_mov_b32_e32 v74, v8
	v_mov_b32_e32 v75, v8
	v_mov_b32_e32 v80, v8
	v_mov_b32_e32 v81, v8
	v_mov_b32_e32 v82, v8
	v_mov_b32_e32 v83, v8
	v_mov_b32_e32 v88, v8
	v_mov_b32_e32 v89, v8
	v_mov_b32_e32 v90, v8
	v_mov_b32_e32 v91, v8
	v_mov_b32_e32 v96, v8
	v_mov_b32_e32 v97, v8
	v_mov_b32_e32 v98, v8
	v_mov_b32_e32 v99, v8
	v_mov_b32_e32 v108, v8
	v_mov_b32_e32 v109, v8
	v_mov_b32_e32 v110, v8
	v_mov_b32_e32 v111, v8
	v_mov_b32_e32 v116, v8
	v_mov_b32_e32 v117, v8
	v_mov_b32_e32 v118, v8
	v_mov_b32_e32 v119, v8
	v_mov_b32_e32 v124, v8
	v_mov_b32_e32 v125, v8
	v_mov_b32_e32 v126, v8
	v_mov_b32_e32 v127, v8
	v_mov_b32_e32 v132, v8
	v_mov_b32_e32 v133, v8
	v_mov_b32_e32 v134, v8
	v_mov_b32_e32 v135, v8
	v_mov_b32_e32 v76, v8
	v_mov_b32_e32 v77, v8
	v_mov_b32_e32 v78, v8
	v_mov_b32_e32 v79, v8
	v_mov_b32_e32 v84, v8
	v_mov_b32_e32 v85, v8
	v_mov_b32_e32 v86, v8
	v_mov_b32_e32 v87, v8
	v_mov_b32_e32 v92, v8
	v_mov_b32_e32 v93, v8
	v_mov_b32_e32 v94, v8
	v_mov_b32_e32 v95, v8
	v_mov_b32_e32 v100, v8
	v_mov_b32_e32 v101, v8
	v_mov_b32_e32 v102, v8
	v_mov_b32_e32 v103, v8
	v_mov_b32_e32 v112, v8
	v_mov_b32_e32 v113, v8
	v_mov_b32_e32 v114, v8
	v_mov_b32_e32 v115, v8
	v_mov_b32_e32 v120, v8
	v_mov_b32_e32 v121, v8
	v_mov_b32_e32 v122, v8
	v_mov_b32_e32 v123, v8
	v_mov_b32_e32 v128, v8
	v_mov_b32_e32 v129, v8
	v_mov_b32_e32 v130, v8
	v_mov_b32_e32 v131, v8
	v_mov_b32_e32 v136, v8
	v_mov_b32_e32 v137, v8
	v_mov_b32_e32 v138, v8
	v_mov_b32_e32 v139, v8
	s_add_u32 s16, s8, 0xfffc0080
	s_addc_u32 s17, s9, -1
	s_cmp_eq_u32 s55, 12
	s_cselect_b32 s43, s14, s17
	s_cselect_b32 s42, s15, s16
	s_cselect_b32 s41, s13, s54
	s_cselect_b32 s40, s25, s53
.LBB0_257:
	s_add_i32 s18, 0, 0x10000
	v_add_u32_e32 v0, s18, v210
	s_add_i32 s19, 0, 0x14000
	ds_read_b128 v[104:107], v0
	ds_read_b128 v[140:143], v0 offset:1024
	ds_read_b128 v[144:147], v0 offset:2048
	ds_read_b128 v[148:151], v0 offset:3072
	v_add_u32_e32 v0, s19, v210
	ds_read_b128 v[152:155], v0
	ds_read_b128 v[156:159], v0 offset:1024
	ds_read_b128 v[160:163], v0 offset:2048
	ds_read_b128 v[192:195], v0 offset:3072
	v_lshl_add_u64 v[2:3], s[8:9], 0, v[188:189]
	s_add_i32 m0, s44, 0xc000
	ds_read_b128 v[196:199], v212
	ds_read_b128 v[214:217], v212 offset:1024
	ds_read_b128 v[218:221], v212 offset:2048
	ds_read_b128 v[222:225], v212 offset:3072
	ds_read_b128 v[226:229], v212 offset:4096
	ds_read_b128 v[230:233], v212 offset:5120
	ds_read_b128 v[234:237], v212 offset:6144
	ds_read_b128 v[238:241], v212 offset:7168
	global_load_lds_dwordx4 v[2:3], off
	v_lshl_add_u64 v[2:3], s[8:9], 0, v[190:191]
	s_add_i32 m0, s44, 0xe000
	s_nop 0
	global_load_lds_dwordx4 v[2:3], off
	s_waitcnt vmcnt(8)
	s_waitcnt lgkmcnt(0)
	s_barrier
; #define PG8_STAGE(bufoff, gbase, voff) do { _Pragma("unroll") for (int _i = 0; _i < 2; ++_i) \
;         __builtin_amdgcn_global_load_lds((const unsigned*)((const char*)(gbase) + (voff)[_i]), (PG8_LAS unsigned*)(lds + (bufoff) + ldsw + _i * 8192), 16, 0, 0); } while (0)
; #define PG8_LDA(dst, b, h) do { _Pragma("unroll") for (int m = 0; m < 4; ++m) _Pragma("unroll") for (int k = 0; k < 2; ++k) dst[m][k] = *(const PG8_LAS bf16x8*)(lds + PG8_SA(b, h) + aoff + m * 2048 + k * 1024); } while (0)
; #define PG8_MMA(ai, bj, At, Bt) do { __builtin_amdgcn_s_setprio(1); _Pragma("unroll") for (int m = 0; m < 4; ++m) _Pragma("unroll") for (int n = 0; n < 2; ++n) _Pragma("unroll") for (int k = 0; k < 2; ++k) \
;         acc[ai][bj][m][n] = __builtin_amdgcn_mfma_f32_16x16x32_bf16(Bt[n][k], At[m][k], acc[ai][bj][m][n], 0, 0, 0); __builtin_amdgcn_s_setprio(0); } while (0)
; #define PG8_WAIT_V(n) asm volatile("s_waitcnt vmcnt(" #n ")" ::: "memory")
; #define PG8_WAIT_L(n) asm volatile("s_waitcnt lgkmcnt(" #n ")" ::: "memory")
; #define PG8_BAR __builtin_amdgcn_s_barrier()
; #define PG8_SCHED __builtin_amdgcn_sched_barrier(0)
; template <class Epi, class Sched, bool ALIGN_EPI = false, bool SP2 = false>
; __device__ __forceinline__ void gemm_phase(PG8_LAS unsigned char* lds, const Gemm g, const Sched& S, const Epi& E) {
;     ...
;             PG8_WAIT_V(8); PG8_WAIT_L(0); PG8_BAR; PG8_MMA(0, 0, At, B0); PG8_MMA(0, 1, At, B1); PG8_BAR; PG8_SCHED;
;             PG8_LDA(At, 0, 1); PG8_STAGE(PG8_SB(0, 0), b2, voffB); PG8_STAGE(PG8_SB(0, 1), b2 + hstep, voffB); PG8_STAGE(PG8_SA(0, 0), a2, voffA);
;             PG8_WAIT_V(8); PG8_WAIT_L(0); PG8_BAR; PG8_MMA(1, 0, At, B0); PG8_MMA(1, 1, At, B1); PG8_BAR; PG8_SCHED;
	s_waitcnt lgkmcnt(0)
	v_mfma_f32_16x16x32_bf16 v[136:139], v[104:107], v[196:199], v[136:139]
	v_mfma_f32_16x16x32_bf16 v[128:131], v[144:147], v[196:199], v[128:131]
	v_mfma_f32_16x16x32_bf16 v[120:123], v[104:107], v[218:221], v[120:123]
	v_mfma_f32_16x16x32_bf16 v[112:115], v[144:147], v[218:221], v[112:115]
	s_setprio 1
	v_mfma_f32_16x16x32_bf16 v[100:103], v[104:107], v[226:229], v[100:103]
	v_mfma_f32_16x16x32_bf16 v[92:95], v[144:147], v[226:229], v[92:95]
	v_mfma_f32_16x16x32_bf16 v[84:87], v[104:107], v[234:237], v[84:87]
	v_mfma_f32_16x16x32_bf16 v[76:79], v[144:147], v[234:237], v[76:79]
	v_mfma_f32_16x16x32_bf16 v[136:139], v[140:143], v[214:217], v[136:139]
	v_mfma_f32_16x16x32_bf16 v[128:131], v[148:151], v[214:217], v[128:131]
	v_mfma_f32_16x16x32_bf16 v[120:123], v[140:143], v[222:225], v[120:123]
	v_mfma_f32_16x16x32_bf16 v[112:115], v[148:151], v[222:225], v[112:115]
	v_mfma_f32_16x16x32_bf16 v[100:103], v[140:143], v[230:233], v[100:103]
	v_mfma_f32_16x16x32_bf16 v[92:95], v[148:151], v[230:233], v[92:95]
	v_mfma_f32_16x16x32_bf16 v[84:87], v[140:143], v[238:241], v[84:87]
	v_mfma_f32_16x16x32_bf16 v[76:79], v[148:151], v[238:241], v[76:79]
	s_setprio 0
	s_setprio 1
	v_mfma_f32_16x16x32_bf16 v[132:135], v[152:155], v[196:199], v[132:135]
	v_mfma_f32_16x16x32_bf16 v[124:127], v[160:163], v[196:199], v[124:127]
	v_mfma_f32_16x16x32_bf16 v[116:119], v[152:155], v[218:221], v[116:119]
	v_mfma_f32_16x16x32_bf16 v[108:111], v[160:163], v[218:221], v[108:111]
	v_mfma_f32_16x16x32_bf16 v[96:99], v[152:155], v[226:229], v[96:99]
	v_mfma_f32_16x16x32_bf16 v[88:91], v[160:163], v[226:229], v[88:91]
	v_mfma_f32_16x16x32_bf16 v[80:83], v[152:155], v[234:237], v[80:83]
	v_mfma_f32_16x16x32_bf16 v[72:75], v[160:163], v[234:237], v[72:75]
	v_mfma_f32_16x16x32_bf16 v[132:135], v[156:159], v[214:217], v[132:135]
	v_mfma_f32_16x16x32_bf16 v[124:127], v[192:195], v[214:217], v[124:127]
	v_mfma_f32_16x16x32_bf16 v[116:119], v[156:159], v[222:225], v[116:119]
	v_mfma_f32_16x16x32_bf16 v[108:111], v[192:195], v[222:225], v[108:111]
	s_barrier
	v_mfma_f32_16x16x32_bf16 v[96:99], v[156:159], v[230:233], v[96:99]
	v_mfma_f32_16x16x32_bf16 v[88:91], v[192:195], v[230:233], v[88:91]
	v_mfma_f32_16x16x32_bf16 v[80:83], v[156:159], v[238:241], v[80:83]
	v_mfma_f32_16x16x32_bf16 v[72:75], v[192:195], v[238:241], v[72:75]
	s_setprio 0
	s_add_i32 s16, s18, s36
	v_lshl_add_u64 v[2:3], s[40:41], 0, v[182:183]
	s_mov_b32 m0, s16
	ds_read_b128 v[196:199], v212 offset:16384
	ds_read_b128 v[214:217], v212 offset:17408
	ds_read_b128 v[218:221], v212 offset:18432
	ds_read_b128 v[222:225], v212 offset:19456
	ds_read_b128 v[226:229], v212 offset:20480
	ds_read_b128 v[230:233], v212 offset:21504
	ds_read_b128 v[234:237], v212 offset:22528
	ds_read_b128 v[238:241], v212 offset:23552
	global_load_lds_dwordx4 v[2:3], off
	s_add_i32 m0, s16, 0x2000
	s_add_u32 s16, s40, 0x40000
	v_lshl_add_u64 v[200:201], s[40:41], 0, v[178:179]
	s_addc_u32 s17, s41, 0
	s_add_i32 s18, s19, s36
	global_load_lds_dwordx4 v[200:201], off
	v_lshl_add_u64 v[242:243], s[16:17], 0, v[182:183]
	s_mov_b32 m0, s18
	v_lshl_add_u64 v[244:245], s[42:43], 0, v[180:181]
	global_load_lds_dwordx4 v[242:243], off
	v_lshl_add_u64 v[242:243], s[16:17], 0, v[178:179]
	s_add_i32 m0, s18, 0x2000
	s_nop 0
	global_load_lds_dwordx4 v[242:243], off
	v_lshl_add_u64 v[242:243], s[42:43], 0, v[184:185]
	s_waitcnt vmcnt(6)
	s_waitcnt lgkmcnt(0)
	s_barrier
	s_waitcnt lgkmcnt(0)
	v_mfma_f32_16x16x32_bf16 v[68:71], v[104:107], v[196:199], v[68:71]
	v_mfma_f32_16x16x32_bf16 v[60:63], v[144:147], v[196:199], v[60:63]
	v_mfma_f32_16x16x32_bf16 v[52:55], v[104:107], v[218:221], v[52:55]
	s_mov_b32 m0, s44
	v_mfma_f32_16x16x32_bf16 v[44:47], v[144:147], v[218:221], v[44:47]
	s_setprio 1
	global_load_lds_dwordx4 v[242:243], off
	v_mfma_f32_16x16x32_bf16 v[36:39], v[104:107], v[226:229], v[36:39]
	v_mfma_f32_16x16x32_bf16 v[28:31], v[144:147], v[226:229], v[28:31]
	v_mfma_f32_16x16x32_bf16 v[20:23], v[104:107], v[234:237], v[20:23]
	v_mfma_f32_16x16x32_bf16 v[12:15], v[144:147], v[234:237], v[12:15]
	v_mfma_f32_16x16x32_bf16 v[68:71], v[140:143], v[214:217], v[68:71]
	v_mfma_f32_16x16x32_bf16 v[60:63], v[148:151], v[214:217], v[60:63]
	v_mfma_f32_16x16x32_bf16 v[52:55], v[140:143], v[222:225], v[52:55]
	s_mov_b32 m0, s45
	v_mfma_f32_16x16x32_bf16 v[44:47], v[148:151], v[222:225], v[44:47]
	global_load_lds_dwordx4 v[244:245], off
	v_mfma_f32_16x16x32_bf16 v[36:39], v[140:143], v[230:233], v[36:39]
	v_mfma_f32_16x16x32_bf16 v[28:31], v[148:151], v[230:233], v[28:31]
	v_mfma_f32_16x16x32_bf16 v[20:23], v[140:143], v[238:241], v[20:23]
	v_mfma_f32_16x16x32_bf16 v[12:15], v[148:151], v[238:241], v[12:15]
	s_setprio 0
	s_setprio 1
	v_mfma_f32_16x16x32_bf16 v[64:67], v[152:155], v[196:199], v[64:67]
	v_mfma_f32_16x16x32_bf16 v[56:59], v[160:163], v[196:199], v[56:59]
	v_mfma_f32_16x16x32_bf16 v[48:51], v[152:155], v[218:221], v[48:51]
	v_mfma_f32_16x16x32_bf16 v[40:43], v[160:163], v[218:221], v[40:43]
	v_mfma_f32_16x16x32_bf16 v[32:35], v[152:155], v[226:229], v[32:35]
	v_mfma_f32_16x16x32_bf16 v[24:27], v[160:163], v[226:229], v[24:27]
	v_mfma_f32_16x16x32_bf16 v[16:19], v[152:155], v[234:237], v[16:19]
	v_mfma_f32_16x16x32_bf16 v[8:11], v[160:163], v[234:237], v[8:11]
	v_mfma_f32_16x16x32_bf16 v[64:67], v[156:159], v[214:217], v[64:67]
	v_mfma_f32_16x16x32_bf16 v[56:59], v[192:195], v[214:217], v[56:59]
	v_mfma_f32_16x16x32_bf16 v[48:51], v[156:159], v[222:225], v[48:51]
	v_mfma_f32_16x16x32_bf16 v[40:43], v[192:195], v[222:225], v[40:43]
	s_barrier
; #define PG8_STAGE(bufoff, gbase, voff) do { _Pragma("unroll") for (int _i = 0; _i < 2; ++_i) \
;         __builtin_amdgcn_global_load_lds((const unsigned*)((const char*)(gbase) + (voff)[_i]), (PG8_LAS unsigned*)(lds + (bufoff) + ldsw + _i * 8192), 16, 0, 0); } while (0)
; #define PG8_LDA(dst, b, h) do { _Pragma("unroll") for (int m = 0; m < 4; ++m) _Pragma("unroll") for (int k = 0; k < 2; ++k) dst[m][k] = *(const PG8_LAS bf16x8*)(lds + PG8_SA(b, h) + aoff + m * 2048 + k * 1024); } while (0)
; #define PG8_LDB(dst, b, h) do { _Pragma("unroll") for (int n = 0; n < 2; ++n) _Pragma("unroll") for (int k = 0; k < 2; ++k) dst[n][k] = *(const PG8_LAS bf16x8*)(lds + PG8_SB(b, h) + boff + n * 2048 + k * 1024); } while (0)
; #define PG8_MMA(ai, bj, At, Bt) do { __builtin_amdgcn_s_setprio(1); _Pragma("unroll") for (int m = 0; m < 4; ++m) _Pragma("unroll") for (int n = 0; n < 2; ++n) _Pragma("unroll") for (int k = 0; k < 2; ++k) \
;         acc[ai][bj][m][n] = __builtin_amdgcn_mfma_f32_16x16x32_bf16(Bt[n][k], At[m][k], acc[ai][bj][m][n], 0, 0, 0); __builtin_amdgcn_s_setprio(0); } while (0)
; #define PG8_WAIT_V(n) asm volatile("s_waitcnt vmcnt(" #n ")" ::: "memory")
; #define PG8_WAIT_L(n) asm volatile("s_waitcnt lgkmcnt(" #n ")" ::: "memory")
; #define PG8_BAR __builtin_amdgcn_s_barrier()
; #define PG8_SCHED __builtin_amdgcn_sched_barrier(0)
; template <class Epi, class Sched, bool ALIGN_EPI = false, bool SP2 = false>
; __device__ __forceinline__ void gemm_phase(PG8_LAS unsigned char* lds, const Gemm g, const Sched& S, const Epi& E) {
;     ...
;             PG8_LDB(B0, 1, 0); PG8_LDB(B1, 1, 1); PG8_SCHED; PG8_LDA(At, 1, 0); PG8_STAGE(PG8_SA(0, 1), a2 + hstep, voffA);
;             PG8_WAIT_V(8); PG8_WAIT_L(0); PG8_BAR; PG8_MMA(0, 0, At, B0); PG8_MMA(0, 1, At, B1); PG8_BAR; PG8_SCHED;
	v_mfma_f32_16x16x32_bf16 v[32:35], v[156:159], v[230:233], v[32:35]
	v_mfma_f32_16x16x32_bf16 v[24:27], v[192:195], v[230:233], v[24:27]
	v_mfma_f32_16x16x32_bf16 v[16:19], v[156:159], v[238:241], v[16:19]
	v_mfma_f32_16x16x32_bf16 v[8:11], v[192:195], v[238:241], v[8:11]
	s_setprio 0
	s_add_i32 s18, 0, 0x18000
	v_add_u32_e32 v0, s18, v210
	ds_read_b128 v[104:107], v0
	ds_read_b128 v[140:143], v0 offset:1024
	ds_read_b128 v[144:147], v0 offset:2048
	ds_read_b128 v[148:151], v0 offset:3072
	v_add_u32_e32 v0, s33, v210
	ds_read_b128 v[152:155], v0
	ds_read_b128 v[156:159], v0 offset:1024
	ds_read_b128 v[160:163], v0 offset:2048
	ds_read_b128 v[192:195], v0 offset:3072
	s_add_u32 s16, s42, 0x40000
	s_addc_u32 s17, s43, 0
	s_mov_b32 m0, s46
	v_lshl_add_u64 v[246:247], s[16:17], 0, v[184:185]
	ds_read_b128 v[196:199], v212 offset:32768
	ds_read_b128 v[214:217], v212 offset:33792
	ds_read_b128 v[218:221], v212 offset:34816
	ds_read_b128 v[222:225], v212 offset:35840
	ds_read_b128 v[226:229], v212 offset:36864
	ds_read_b128 v[230:233], v212 offset:37888
	ds_read_b128 v[234:237], v212 offset:38912
	ds_read_b128 v[238:241], v212 offset:39936
	global_load_lds_dwordx4 v[246:247], off
	v_lshl_add_u64 v[246:247], s[16:17], 0, v[180:181]
	s_mov_b32 m0, s47
	s_nop 0
	global_load_lds_dwordx4 v[246:247], off
	s_waitcnt vmcnt(8)
	s_waitcnt lgkmcnt(0)
	s_barrier
	s_waitcnt lgkmcnt(0)
	v_mfma_f32_16x16x32_bf16 v[136:139], v[104:107], v[196:199], v[136:139]
	v_mfma_f32_16x16x32_bf16 v[128:131], v[144:147], v[196:199], v[128:131]
	v_mfma_f32_16x16x32_bf16 v[120:123], v[104:107], v[218:221], v[120:123]
	v_mfma_f32_16x16x32_bf16 v[112:115], v[144:147], v[218:221], v[112:115]
	s_setprio 1
	v_mfma_f32_16x16x32_bf16 v[100:103], v[104:107], v[226:229], v[100:103]
	v_mfma_f32_16x16x32_bf16 v[92:95], v[144:147], v[226:229], v[92:95]
	v_mfma_f32_16x16x32_bf16 v[84:87], v[104:107], v[234:237], v[84:87]
	v_mfma_f32_16x16x32_bf16 v[76:79], v[144:147], v[234:237], v[76:79]
	v_mfma_f32_16x16x32_bf16 v[136:139], v[140:143], v[214:217], v[136:139]
	v_mfma_f32_16x16x32_bf16 v[128:131], v[148:151], v[214:217], v[128:131]
	v_mfma_f32_16x16x32_bf16 v[120:123], v[140:143], v[222:225], v[120:123]
	v_mfma_f32_16x16x32_bf16 v[112:115], v[148:151], v[222:225], v[112:115]
	v_mfma_f32_16x16x32_bf16 v[100:103], v[140:143], v[230:233], v[100:103]
	v_mfma_f32_16x16x32_bf16 v[92:95], v[148:151], v[230:233], v[92:95]
	v_mfma_f32_16x16x32_bf16 v[84:87], v[140:143], v[238:241], v[84:87]
	v_mfma_f32_16x16x32_bf16 v[76:79], v[148:151], v[238:241], v[76:79]
	s_setprio 0
	s_setprio 1
	v_mfma_f32_16x16x32_bf16 v[132:135], v[152:155], v[196:199], v[132:135]
	v_mfma_f32_16x16x32_bf16 v[124:127], v[160:163], v[196:199], v[124:127]
	v_mfma_f32_16x16x32_bf16 v[116:119], v[152:155], v[218:221], v[116:119]
	v_mfma_f32_16x16x32_bf16 v[108:111], v[160:163], v[218:221], v[108:111]
	v_mfma_f32_16x16x32_bf16 v[96:99], v[152:155], v[226:229], v[96:99]
	v_mfma_f32_16x16x32_bf16 v[88:91], v[160:163], v[226:229], v[88:91]
	v_mfma_f32_16x16x32_bf16 v[80:83], v[152:155], v[234:237], v[80:83]
	v_mfma_f32_16x16x32_bf16 v[72:75], v[160:163], v[234:237], v[72:75]
	v_mfma_f32_16x16x32_bf16 v[132:135], v[156:159], v[214:217], v[132:135]
	v_mfma_f32_16x16x32_bf16 v[124:127], v[192:195], v[214:217], v[124:127]
	v_mfma_f32_16x16x32_bf16 v[116:119], v[156:159], v[222:225], v[116:119]
	v_mfma_f32_16x16x32_bf16 v[108:111], v[192:195], v[222:225], v[108:111]
	s_barrier
; #define PG8_STAGE(bufoff, gbase, voff) do { _Pragma("unroll") for (int _i = 0; _i < 2; ++_i) \
;         __builtin_amdgcn_global_load_lds((const unsigned*)((const char*)(gbase) + (voff)[_i]), (PG8_LAS unsigned*)(lds + (bufoff) + ldsw + _i * 8192), 16, 0, 0); } while (0)
; #define PG8_LDA(dst, b, h) do { _Pragma("unroll") for (int m = 0; m < 4; ++m) _Pragma("unroll") for (int k = 0; k < 2; ++k) dst[m][k] = *(const PG8_LAS bf16x8*)(lds + PG8_SA(b, h) + aoff + m * 2048 + k * 1024); } while (0)
; #define PG8_MMA(ai, bj, At, Bt) do { __builtin_amdgcn_s_setprio(1); _Pragma("unroll") for (int m = 0; m < 4; ++m) _Pragma("unroll") for (int n = 0; n < 2; ++n) _Pragma("unroll") for (int k = 0; k < 2; ++k) \
;         acc[ai][bj][m][n] = __builtin_amdgcn_mfma_f32_16x16x32_bf16(Bt[n][k], At[m][k], acc[ai][bj][m][n], 0, 0, 0); __builtin_amdgcn_s_setprio(0); } while (0)
; #define PG8_WAIT_V(n) asm volatile("s_waitcnt vmcnt(" #n ")" ::: "memory")
; #define PG8_WAIT_L(n) asm volatile("s_waitcnt lgkmcnt(" #n ")" ::: "memory")
; #define PG8_BAR __builtin_amdgcn_s_barrier()
; #define PG8_SCHED __builtin_amdgcn_sched_barrier(0)
; template <class Epi, class Sched, bool ALIGN_EPI = false, bool SP2 = false>
; __device__ __forceinline__ void gemm_phase(PG8_LAS unsigned char* lds, const Gemm g, const Sched& S, const Epi& E) {
;     ...
;         for (int t = 0; t < nt; t += 2) {
;             const bool last = (t == nt - 2);
;             const char* a1 = cA + (size_t)(t + 1) * kstep;
;             const char* a2 = last ? nA : cA + (size_t)(t + 2) * kstep; const char* b2 = last ? nB : cB + (size_t)(t + 2) * kstep;
;             const char* a3 = a2 + kstep; const char* b3 = b2 + kstep;
;     ...
;             PG8_LDA(At, 1, 1); PG8_STAGE(PG8_SB(1, 0), b3, voffB); PG8_STAGE(PG8_SB(1, 1), b3 + hstep, voffB); PG8_STAGE(PG8_SA(1, 0), a3, voffA);
;             PG8_WAIT_V(8); PG8_WAIT_L(0); PG8_BAR; PG8_MMA(1, 0, At, B0); PG8_MMA(1, 1, At, B1); PG8_BAR; PG8_SCHED;
	v_mfma_f32_16x16x32_bf16 v[96:99], v[156:159], v[230:233], v[96:99]
	v_mfma_f32_16x16x32_bf16 v[88:91], v[192:195], v[230:233], v[88:91]
	v_mfma_f32_16x16x32_bf16 v[80:83], v[156:159], v[238:241], v[80:83]
	v_mfma_f32_16x16x32_bf16 v[72:75], v[192:195], v[238:241], v[72:75]
	s_setprio 0
	s_add_i32 s16, s18, s36
	v_lshl_add_u64 v[2:3], v[2:3], 0, s[20:21]
	s_mov_b32 m0, s16
	ds_read_b128 v[196:199], v212 offset:49152
	ds_read_b128 v[214:217], v212 offset:50176
	ds_read_b128 v[218:221], v212 offset:51200
	ds_read_b128 v[222:225], v212 offset:52224
	ds_read_b128 v[226:229], v212 offset:53248
	ds_read_b128 v[230:233], v212 offset:54272
	ds_read_b128 v[234:237], v212 offset:55296
	ds_read_b128 v[238:241], v212 offset:56320
	global_load_lds_dwordx4 v[2:3], off
	s_add_i32 m0, s16, 0x2000
	s_add_u32 s16, s40, 0x40080
	v_lshl_add_u64 v[2:3], v[200:201], 0, s[20:21]
	s_addc_u32 s17, s41, 0
	s_add_i32 s18, s33, s36
	global_load_lds_dwordx4 v[2:3], off
	v_lshl_add_u64 v[2:3], s[16:17], 0, v[182:183]
	s_mov_b32 m0, s18
	s_nop 0
	global_load_lds_dwordx4 v[2:3], off
	v_lshl_add_u64 v[2:3], s[16:17], 0, v[178:179]
	s_add_i32 m0, s18, 0x2000
	s_nop 0
	global_load_lds_dwordx4 v[2:3], off
	v_lshl_add_u64 v[2:3], v[242:243], 0, s[20:21]
	v_lshl_add_u64 v[244:245], v[244:245], 0, s[20:21]
	s_waitcnt vmcnt(6)
	s_waitcnt lgkmcnt(0)
	s_barrier
	s_waitcnt lgkmcnt(0)
	v_mfma_f32_16x16x32_bf16 v[68:71], v[104:107], v[196:199], v[68:71]
	v_mfma_f32_16x16x32_bf16 v[60:63], v[144:147], v[196:199], v[60:63]
	v_mfma_f32_16x16x32_bf16 v[52:55], v[104:107], v[218:221], v[52:55]
	s_mov_b32 m0, s48
	v_mfma_f32_16x16x32_bf16 v[44:47], v[144:147], v[218:221], v[44:47]
	s_setprio 1
	global_load_lds_dwordx4 v[2:3], off
	v_mfma_f32_16x16x32_bf16 v[36:39], v[104:107], v[226:229], v[36:39]
	v_mfma_f32_16x16x32_bf16 v[28:31], v[144:147], v[226:229], v[28:31]
	v_mfma_f32_16x16x32_bf16 v[20:23], v[104:107], v[234:237], v[20:23]
	s_add_i32 s55, s55, 2
	v_mfma_f32_16x16x32_bf16 v[12:15], v[144:147], v[234:237], v[12:15]
	s_add_u32 s8, s8, 0x100
	s_addc_u32 s9, s9, 0
	v_mfma_f32_16x16x32_bf16 v[68:71], v[140:143], v[214:217], v[68:71]
	s_add_u32 s53, s53, 0x100
	s_addc_u32 s54, s54, 0
	v_mfma_f32_16x16x32_bf16 v[60:63], v[148:151], v[214:217], v[60:63]
	s_add_u32 s16, s8, 0xfffc0080
	s_addc_u32 s17, s9, -1
	v_mfma_f32_16x16x32_bf16 v[52:55], v[140:143], v[222:225], v[52:55]
	s_cmp_eq_u32 s55, 12
	s_cselect_b32 s43, s14, s17
	s_cselect_b32 s42, s15, s16
	s_mov_b32 m0, s49
	v_mfma_f32_16x16x32_bf16 v[44:47], v[148:151], v[222:225], v[44:47]
	s_cselect_b32 s41, s13, s54
	s_cselect_b32 s40, s25, s53
	global_load_lds_dwordx4 v[244:245], off
	v_mfma_f32_16x16x32_bf16 v[36:39], v[140:143], v[230:233], v[36:39]
	v_mfma_f32_16x16x32_bf16 v[28:31], v[148:151], v[230:233], v[28:31]
	v_mfma_f32_16x16x32_bf16 v[20:23], v[140:143], v[238:241], v[20:23]
	v_mfma_f32_16x16x32_bf16 v[12:15], v[148:151], v[238:241], v[12:15]
	s_setprio 0
	s_setprio 1
	v_mfma_f32_16x16x32_bf16 v[64:67], v[152:155], v[196:199], v[64:67]
	v_mfma_f32_16x16x32_bf16 v[56:59], v[160:163], v[196:199], v[56:59]
	v_mfma_f32_16x16x32_bf16 v[48:51], v[152:155], v[218:221], v[48:51]
	v_mfma_f32_16x16x32_bf16 v[40:43], v[160:163], v[218:221], v[40:43]
	v_mfma_f32_16x16x32_bf16 v[32:35], v[152:155], v[226:229], v[32:35]
	v_mfma_f32_16x16x32_bf16 v[24:27], v[160:163], v[226:229], v[24:27]
	v_mfma_f32_16x16x32_bf16 v[16:19], v[152:155], v[234:237], v[16:19]
	v_mfma_f32_16x16x32_bf16 v[8:11], v[160:163], v[234:237], v[8:11]
	v_mfma_f32_16x16x32_bf16 v[64:67], v[156:159], v[214:217], v[64:67]
	v_mfma_f32_16x16x32_bf16 v[56:59], v[192:195], v[214:217], v[56:59]
	v_mfma_f32_16x16x32_bf16 v[48:51], v[156:159], v[222:225], v[48:51]
	v_mfma_f32_16x16x32_bf16 v[40:43], v[192:195], v[222:225], v[40:43]
	s_barrier
	v_mfma_f32_16x16x32_bf16 v[32:35], v[156:159], v[230:233], v[32:35]
	v_mfma_f32_16x16x32_bf16 v[24:27], v[192:195], v[230:233], v[24:27]
	v_mfma_f32_16x16x32_bf16 v[16:19], v[156:159], v[238:241], v[16:19]
	v_mfma_f32_16x16x32_bf16 v[8:11], v[192:195], v[238:241], v[8:11]
	s_setprio 0
	s_cmp_gt_u32 s55, 13
	s_cbranch_scc0 .LBB0_257
	s_and_b64 vcc, exec, s[10:11]
	s_cbranch_vccz .LBB0_260
	s_barrier
	s_setprio 1
